# baseline (speedup 1.0000x reference)
.LBB0_1:
	v_readlane_b32 s0, v255, 0
	v_readlane_b32 s1, v255, 1
	s_add_u32 s86, s0, 0xe8
	v_and_b32_e32 v131, 0x3ff, v0
	s_addc_u32 s87, s1, 0
	s_load_dword s83, s[0:1], 0xe8
	v_cmp_eq_u32_e64 s[0:1], 0, v131
	v_and_b32_e32 v0, 0x3fffffff, v0
	s_mov_b32 s73, s2
	v_writelane_b32 v255, s0, 4
	s_mov_b32 s35, 0
	v_mov_b32_e32 v129, 0
	v_writelane_b32 v255, s1, 5
	s_and_b32 s0, s2, 7
	s_xor_b32 s1, s0, 7
	v_writelane_b32 v255, s1, 6
	v_cmp_eq_u32_e64 s[2:3], 0, v0
	s_lshl_b32 s0, s0, 6
	s_lshl_b32 s0, s0, 2
	v_writelane_b32 v255, s2, 7
	v_mov_b32_e32 v130, 0x358637bd
	s_mov_b32 s89, 0x800000
	v_writelane_b32 v255, s3, 8
	v_writelane_b32 v255, s0, 9
	s_movk_i32 s34, 0x2000
	v_readlane_b32 s0, v255, 2
	v_readlane_b32 s1, v255, 3
	v_writelane_b32 v255, s73, 10
	v_writelane_b32 v255, s86, 11
	s_mov_b64 s[44:45], 0x80
	s_mov_b32 s33, 0x42ce8ed0
	s_mov_b32 s90, 0xc2b17218
	s_mov_b32 s92, 0x3f2aaaab
	v_mov_b32_e32 v174, 0x3ecc95a3
	s_mov_b32 s93, 0x3f317218
	s_mov_b32 s30, 0x33800000
	s_movk_i32 s31, 0x5800
	v_mov_b32_e32 v175, 0x7f800000
	v_mov_b32_e32 v176, 0xff800000
	v_mov_b32_e32 v254, 0xfffff500
	v_mov_b32_e32 v177, 0x80
	s_mov_b32 s10, s0
	s_mov_b64 s[48:49], 0x40080
	s_mov_b64 s[50:51], 0x60080
	s_mov_b64 s[52:53], 0x100
	s_mov_b64 s[54:55], 0x20100
	s_mov_b64 s[56:57], 0x40100
	s_mov_b64 s[58:59], 0x60100
	s_mov_b64 s[60:61], 0x180
	s_mov_b64 s[62:63], 0x20180
	s_mov_b64 s[64:65], 0x40180
	s_mov_b64 s[66:67], 0x60180
	s_mov_b32 s72, 0xbfb8aa3b
	s_mov_b64 s[94:95], 0x58100
	s_mov_b64 s[96:97], 0xb0100
	s_mov_b64 s[74:75], 0x108100
	s_mov_b64 s[20:21], 0x58180
	s_mov_b64 s[4:5], 0x200
	s_mov_b32 s82, 0x3e38aa3b
	s_mov_b32 s88, 0x3dd2d3e7
	s_mov_b64 s[84:85], 0x800
	v_writelane_b32 v255, s87, 12
	s_mov_b32 s100, 0
	s_branch .LBB0_6

.LBB0_2676:
	v_readlane_b32 s2, v255, 17
	s_cmp_lg_u32 s100, 0
	s_cbranch_scc1 .Lrep_done
	s_mov_b32 s101, 0x22
	s_bitcmp1_b32 s101, s2
	s_cbranch_scc0 .Lrep_none
	s_mov_b32 s100, 1
	s_mov_b32 s10, s2
	s_waitcnt vmcnt(0) lgkmcnt(0)
	s_barrier
	s_mov_b64 s[0:1], 0
	s_branch .LBB0_2699
.Lrep_done:
	s_mov_b32 s100, 0
